# speedup vs baseline: 1.1290x; 1.0239x over previous
; DEV f32x16 mfma(bf16x8 a, bf16x8 b, f32x16 c) { return __builtin_amdgcn_mfma_f32_32x32x16_bf16(a, b, c, 0, 0, 0); }
;     ...
;   for (int kt = 0; kt < nk; ++kt) {
;     if (kt + 1 < nk) { if (MI == 4) asm volatile("s_waitcnt vmcnt(6)" ::: "memory"); else asm volatile("s_waitcnt vmcnt(4)" ::: "memory"); } else asm volatile("s_waitcnt vmcnt(0)" ::: "memory");
;     __builtin_amdgcn_s_barrier();
;     if (kt + 2 < nk) { int s2 = stg + 2; if (s2 >= 3) s2 -= 3; g2_issue<MI>(ag + (size_t)(kt + 2) * 32, bg + (size_t)(kt + 2) * 32, lda, ldb, voffa, voffb, lds + s2 * G2_STAGE, w); }
;     const unsigned so = (unsigned)(stg * G2_STAGE);
;     __builtin_amdgcn_s_setprio(1);
; #pragma unroll
;     for (int ks = 0; ks < 2; ++ks) {
;       const unsigned aa = (ks ? la1 : la0) + so, bb = (ks ? lb1 : lb0) + so;
;       bf16x8 fb0, fb1, fa0, fa1, fa2, fa3;
;       asm volatile("ds_read_b128 %0, %1" : "=v"(fb0) : "v"(bb));
;       asm volatile("ds_read_b128 %0, %1 offset:2048" : "=v"(fb1) : "v"(bb));
;       asm volatile("ds_read_b128 %0, %1" : "=v"(fa0) : "v"(aa));
;       asm volatile("ds_read_b128 %0, %1 offset:2048" : "=v"(fa1) : "v"(aa));
;       if constexpr (MI == 4) {
;         asm volatile("ds_read_b128 %0, %1 offset:4096" : "=v"(fa2) : "v"(aa));
;         asm volatile("ds_read_b128 %0, %1 offset:6144" : "=v"(fa3) : "v"(aa));
;         __builtin_amdgcn_sched_barrier(0);
;         asm volatile("s_waitcnt lgkmcnt(3)" : "+v"(fb0), "+v"(fb1), "+v"(fa0));
;         acc[0][0][0] = mfma(fa0, fb0, acc[0][0][0]); acc[0][0][1] = mfma(fa0, fb1, acc[0][0][1]); __builtin_amdgcn_sched_barrier(0);
;         asm volatile("s_waitcnt lgkmcnt(2)" : "+v"(fa1));
;         acc[0][1][0] = mfma(fa1, fb0, acc[0][1][0]); acc[0][1][1] = mfma(fa1, fb1, acc[0][1][1]); __builtin_amdgcn_sched_barrier(0);
;         asm volatile("s_waitcnt lgkmcnt(1)" : "+v"(fa2));
;         acc[MI / 2 - 1][0][0] = mfma(fa2, fb0, acc[MI / 2 - 1][0][0]); acc[MI / 2 - 1][0][1] = mfma(fa2, fb1, acc[MI / 2 - 1][0][1]); __builtin_amdgcn_sched_barrier(0);
;         asm volatile("s_waitcnt lgkmcnt(0)" : "+v"(fa3));
;         acc[MI / 2 - 1][1][0] = mfma(fa3, fb0, acc[MI / 2 - 1][1][0]); acc[MI / 2 - 1][1][1] = mfma(fa3, fb1, acc[MI / 2 - 1][1][1]); __builtin_amdgcn_sched_barrier(0);
.LBB0_79:
	s_cmp_gt_i32 s6, 0
	s_cselect_b32 s81, -1, 2
	s_add_i32 s81, s81, s6
	s_mulk_i32 s81, 0x6000
	s_add_u32 s82, s7, s18
	s_addc_u32 s83, s80, s19
	s_add_i32 s84, s59, s81
	s_cmp_eq_u32 s18, 0
	s_cbranch_scc1 .Lhy7_first_down
	s_waitcnt vmcnt(0)
	s_barrier
	s_mul_i32 s99, s6, 0x6000
	s_setprio 1
	v_add_u32_e32 v147, s99, v141
	v_add_u32_e32 v149, s99, v143
	v_add_u32_e32 v172, v147, v145
	v_add_u32_e32 v156, v149, v145
	ds_read_b128 v[152:155], v156
	ds_read_b128 v[156:159], v156 offset:2048
	ds_read_b128 v[160:163], v172
	ds_read_b128 v[164:167], v172 offset:2048
	ds_read_b128 v[168:171], v172 offset:4096
	ds_read_b128 v[172:175], v172 offset:6144
	v_add_u32_e32 v147, v147, v138
	v_add_u32_e32 v149, v149, v138
	ds_read_b128 v[180:183], v149
	ds_read_b128 v[184:187], v149 offset:2048
	ds_read_b128 v[188:191], v147
	ds_read_b128 v[242:245], v147 offset:2048
	ds_read_b128 v[246:249], v147 offset:4096
	ds_read_b128 v[250:253], v147 offset:6144
	s_add_i32 s98, s6, 1
	s_cmp_lg_u32 s6, 2
	s_cselect_b32 s98, s98, 0
	s_mul_i32 s98, s98, 0x6000
	s_add_i32 s99, s59, s98
	v_add_u32_e32 v238, s99, v254
	ds_write_b128 v238, v[214:217]
	s_add_i32 s99, s58, s98
	v_add_u32_e32 v255, s99, v254
	ds_write_b128 v255, v[218:221]
	s_add_i32 s99, s57, s98
	v_add_u32_e32 v238, s99, v254
	ds_write_b128 v238, v[222:225]
	s_cmpk_eq_i32 s18, 0x2b80
	s_cbranch_scc1 .Lhy7_noissueE_down
	s_mov_b32 m0, s84
	s_nop 0
	global_load_lds_dwordx4 v1, s[82:83]
	global_load_dwordx4 v[214:217], v1, s[82:83] offset:64
	s_nop 0
	s_waitcnt lgkmcnt(9)
	s_nop 0
	v_mfma_f32_32x32x16_bf16 v[114:129], v[160:163], v[152:155], v[114:129]
	v_mfma_f32_32x32x16_bf16 v[98:113], v[160:163], v[156:159], v[98:113]
	s_add_u32 s82, s78, s18
	s_addc_u32 s83, s79, s19
	s_add_i32 s84, s58, s81
	s_mov_b32 m0, s84
	s_nop 0
	global_load_lds_dwordx4 v1, s[82:83]
	global_load_dwordx4 v[218:221], v1, s[82:83] offset:64
	s_waitcnt lgkmcnt(8)
	s_nop 0
	v_mfma_f32_32x32x16_bf16 v[82:97], v[164:167], v[152:155], v[82:97]
	v_mfma_f32_32x32x16_bf16 v[66:81], v[164:167], v[156:159], v[66:81]
	s_add_u32 s82, s76, s18
	s_addc_u32 s83, s77, s19
	s_add_i32 s84, s57, s81
	s_mov_b32 m0, s84
	s_nop 0
	global_load_lds_dwordx4 v1, s[82:83]
	global_load_dwordx4 v[222:225], v1, s[82:83] offset:64
	s_waitcnt lgkmcnt(7)
	s_nop 0
	v_mfma_f32_32x32x16_bf16 v[50:65], v[168:171], v[152:155], v[50:65]
	v_mfma_f32_32x32x16_bf16 v[34:49], v[168:171], v[156:159], v[34:49]
	s_waitcnt lgkmcnt(6)
	s_nop 0
	v_mfma_f32_32x32x16_bf16 v[18:33], v[172:175], v[152:155], v[18:33]
	v_mfma_f32_32x32x16_bf16 v[2:17], v[172:175], v[156:159], v[2:17]
	s_branch .Lhy7_afterE_down

; DEV f32x16 mfma(bf16x8 a, bf16x8 b, f32x16 c) { return __builtin_amdgcn_mfma_f32_32x32x16_bf16(a, b, c, 0, 0, 0); }
;     ...
;     if (kt + 2 < nk) { int s2 = stg + 2; if (s2 >= 3) s2 -= 3; g2_issue<MI>(ag + (size_t)(kt + 2) * 32, bg + (size_t)(kt + 2) * 32, lda, ldb, voffa, voffb, lds + s2 * G2_STAGE, w); }
;     const unsigned so = (unsigned)(stg * G2_STAGE);
;     __builtin_amdgcn_s_setprio(1);
; #pragma unroll
;     for (int ks = 0; ks < 2; ++ks) {
;       const unsigned aa = (ks ? la1 : la0) + so, bb = (ks ? lb1 : lb0) + so;
;       bf16x8 fb0, fb1, fa0, fa1, fa2, fa3;
;       asm volatile("ds_read_b128 %0, %1" : "=v"(fb0) : "v"(bb));
;       asm volatile("ds_read_b128 %0, %1 offset:2048" : "=v"(fb1) : "v"(bb));
;       asm volatile("ds_read_b128 %0, %1" : "=v"(fa0) : "v"(aa));
;       asm volatile("ds_read_b128 %0, %1 offset:2048" : "=v"(fa1) : "v"(aa));
;       if constexpr (MI == 4) {
;         asm volatile("ds_read_b128 %0, %1 offset:4096" : "=v"(fa2) : "v"(aa));
;         asm volatile("ds_read_b128 %0, %1 offset:6144" : "=v"(fa3) : "v"(aa));
;         __builtin_amdgcn_sched_barrier(0);
;         asm volatile("s_waitcnt lgkmcnt(3)" : "+v"(fb0), "+v"(fb1), "+v"(fa0));
;         acc[0][0][0] = mfma(fa0, fb0, acc[0][0][0]); acc[0][0][1] = mfma(fa0, fb1, acc[0][0][1]); __builtin_amdgcn_sched_barrier(0);
;         asm volatile("s_waitcnt lgkmcnt(2)" : "+v"(fa1));
;         acc[0][1][0] = mfma(fa1, fb0, acc[0][1][0]); acc[0][1][1] = mfma(fa1, fb1, acc[0][1][1]); __builtin_amdgcn_sched_barrier(0);
;         asm volatile("s_waitcnt lgkmcnt(1)" : "+v"(fa2));
;         acc[MI / 2 - 1][0][0] = mfma(fa2, fb0, acc[MI / 2 - 1][0][0]); acc[MI / 2 - 1][0][1] = mfma(fa2, fb1, acc[MI / 2 - 1][0][1]); __builtin_amdgcn_sched_barrier(0);
;         asm volatile("s_waitcnt lgkmcnt(0)" : "+v"(fa3));
;         acc[MI / 2 - 1][1][0] = mfma(fa3, fb0, acc[MI / 2 - 1][1][0]); acc[MI / 2 - 1][1][1] = mfma(fa3, fb1, acc[MI / 2 - 1][1][1]); __builtin_amdgcn_sched_barrier(0);
.Lhy7_afterE_down:
	s_nop 0
	s_waitcnt lgkmcnt(6)
	s_nop 0
	v_mfma_f32_32x32x16_bf16 v[114:129], v[188:191], v[180:183], v[114:129]
	v_mfma_f32_32x32x16_bf16 v[98:113], v[188:191], v[184:187], v[98:113]
	s_waitcnt lgkmcnt(5)
	s_nop 0
	v_mfma_f32_32x32x16_bf16 v[82:97], v[242:245], v[180:183], v[82:97]
	v_mfma_f32_32x32x16_bf16 v[66:81], v[242:245], v[184:187], v[66:81]
	s_waitcnt lgkmcnt(4)
	s_nop 0
	v_mfma_f32_32x32x16_bf16 v[50:65], v[246:249], v[180:183], v[50:65]
	v_mfma_f32_32x32x16_bf16 v[34:49], v[246:249], v[184:187], v[34:49]
	s_waitcnt lgkmcnt(3)
	s_nop 0
	v_mfma_f32_32x32x16_bf16 v[18:33], v[250:253], v[180:183], v[18:33]
	v_mfma_f32_32x32x16_bf16 v[2:17], v[250:253], v[184:187], v[2:17]
	s_add_i32 s99, s56, s98
	v_add_u32_e32 v255, s99, v254
	ds_write_b128 v255, v[226:229]
	s_add_i32 s99, s55, s98
	s_addk_i32 s99, 0x4000
	v_add_u32_e32 v238, s99, v254
	ds_write_b128 v238, v[230:233]
	s_add_i32 s99, s54, s98
	s_addk_i32 s99, 0x4000
	v_add_u32_e32 v255, s99, v254
	ds_write_b128 v255, v[234:237]
	s_branch .Lhy7_odd_down
.Lhy7_first_down:
	s_waitcnt vmcnt(6)
	s_barrier
	s_mul_i32 s99, s6, 0x6000
	s_setprio 1
	v_add_u32_e32 v147, s99, v141
	v_add_u32_e32 v149, s99, v143
	v_add_u32_e32 v172, v147, v145
	v_add_u32_e32 v156, v149, v145
	ds_read_b128 v[152:155], v156
	ds_read_b128 v[156:159], v156 offset:2048
	ds_read_b128 v[160:163], v172
	ds_read_b128 v[164:167], v172 offset:2048
	ds_read_b128 v[168:171], v172 offset:4096
	ds_read_b128 v[172:175], v172 offset:6144
	v_add_u32_e32 v147, v147, v138
	v_add_u32_e32 v149, v149, v138
	ds_read_b128 v[180:183], v149
	ds_read_b128 v[184:187], v149 offset:2048
	ds_read_b128 v[188:191], v147
	ds_read_b128 v[242:245], v147 offset:2048
	ds_read_b128 v[246:249], v147 offset:4096
	ds_read_b128 v[250:253], v147 offset:6144
	s_cmpk_eq_i32 s18, 0x2b80
	s_cbranch_scc1 .Lhy7_noissueF_down
	s_mov_b32 m0, s84
	s_nop 0
	global_load_lds_dwordx4 v1, s[82:83]
	global_load_dwordx4 v[214:217], v1, s[82:83] offset:64
	s_nop 0
	s_waitcnt lgkmcnt(9)
	s_nop 0
	v_mfma_f32_32x32x16_bf16 v[114:129], v[160:163], v[152:155], v[114:129]
	v_mfma_f32_32x32x16_bf16 v[98:113], v[160:163], v[156:159], v[98:113]
	s_add_u32 s82, s78, s18
	s_addc_u32 s83, s79, s19
	s_add_i32 s84, s58, s81
	s_mov_b32 m0, s84
	s_nop 0
	global_load_lds_dwordx4 v1, s[82:83]
	global_load_dwordx4 v[218:221], v1, s[82:83] offset:64
	s_waitcnt lgkmcnt(8)
	s_nop 0
	v_mfma_f32_32x32x16_bf16 v[82:97], v[164:167], v[152:155], v[82:97]
	v_mfma_f32_32x32x16_bf16 v[66:81], v[164:167], v[156:159], v[66:81]
	s_add_u32 s82, s76, s18
	s_addc_u32 s83, s77, s19
	s_add_i32 s84, s57, s81
	s_mov_b32 m0, s84
	s_nop 0
	global_load_lds_dwordx4 v1, s[82:83]
	global_load_dwordx4 v[222:225], v1, s[82:83] offset:64
	s_waitcnt lgkmcnt(7)
	s_nop 0
	v_mfma_f32_32x32x16_bf16 v[50:65], v[168:171], v[152:155], v[50:65]
	v_mfma_f32_32x32x16_bf16 v[34:49], v[168:171], v[156:159], v[34:49]
	s_waitcnt lgkmcnt(6)
	s_nop 0
	v_mfma_f32_32x32x16_bf16 v[18:33], v[172:175], v[152:155], v[18:33]
	v_mfma_f32_32x32x16_bf16 v[2:17], v[172:175], v[156:159], v[2:17]
	s_branch .Lhy7_afterF_down

;     ...
;     if (kt + 1 < nk) { if (MI == 4) asm volatile("s_waitcnt vmcnt(6)" ::: "memory"); else asm volatile("s_waitcnt vmcnt(4)" ::: "memory"); } else asm volatile("s_waitcnt vmcnt(0)" ::: "memory");
;     __builtin_amdgcn_s_barrier();
;     if (kt + 2 < nk) { int s2 = stg + 2; if (s2 >= 3) s2 -= 3; g2_issue<MI>(ag + (size_t)(kt + 2) * 32, bg + (size_t)(kt + 2) * 32, lda, ldb, voffa, voffb, lds + s2 * G2_STAGE, w); }
;     const unsigned so = (unsigned)(stg * G2_STAGE);
;     __builtin_amdgcn_s_setprio(1);
; #pragma unroll
;     for (int ks = 0; ks < 2; ++ks) {
;       const unsigned aa = (ks ? la1 : la0) + so, bb = (ks ? lb1 : lb0) + so;
;       bf16x8 fb0, fb1, fa0, fa1, fa2, fa3;
;       asm volatile("ds_read_b128 %0, %1" : "=v"(fb0) : "v"(bb));
;       asm volatile("ds_read_b128 %0, %1 offset:2048" : "=v"(fb1) : "v"(bb));
;       asm volatile("ds_read_b128 %0, %1" : "=v"(fa0) : "v"(aa));
;       asm volatile("ds_read_b128 %0, %1 offset:2048" : "=v"(fa1) : "v"(aa));
;       if constexpr (MI == 4) {
;         asm volatile("ds_read_b128 %0, %1 offset:4096" : "=v"(fa2) : "v"(aa));
;         asm volatile("ds_read_b128 %0, %1 offset:6144" : "=v"(fa3) : "v"(aa));
;         __builtin_amdgcn_sched_barrier(0);
;         asm volatile("s_waitcnt lgkmcnt(3)" : "+v"(fb0), "+v"(fb1), "+v"(fa0));
;         acc[0][0][0] = mfma(fa0, fb0, acc[0][0][0]); acc[0][0][1] = mfma(fa0, fb1, acc[0][0][1]); __builtin_amdgcn_sched_barrier(0);
;         asm volatile("s_waitcnt lgkmcnt(2)" : "+v"(fa1));
;         acc[0][1][0] = mfma(fa1, fb0, acc[0][1][0]); acc[0][1][1] = mfma(fa1, fb1, acc[0][1][1]); __builtin_amdgcn_sched_barrier(0);
;         asm volatile("s_waitcnt lgkmcnt(1)" : "+v"(fa2));
;         acc[MI / 2 - 1][0][0] = mfma(fa2, fb0, acc[MI / 2 - 1][0][0]); acc[MI / 2 - 1][0][1] = mfma(fa2, fb1, acc[MI / 2 - 1][0][1]); __builtin_amdgcn_sched_barrier(0);
;         asm volatile("s_waitcnt lgkmcnt(0)" : "+v"(fa3));
;         acc[MI / 2 - 1][1][0] = mfma(fa3, fb0, acc[MI / 2 - 1][1][0]); acc[MI / 2 - 1][1][1] = mfma(fa3, fb1, acc[MI / 2 - 1][1][1]); __builtin_amdgcn_sched_barrier(0);
;       } else {
;         __builtin_amdgcn_sched_barrier(0);
;         asm volatile("s_waitcnt lgkmcnt(1)" : "+v"(fb0), "+v"(fb1), "+v"(fa0));
;         acc[0][0][0] = mfma(fa0, fb0, acc[0][0][0]); acc[0][0][1] = mfma(fa0, fb1, acc[0][0][1]); __builtin_amdgcn_sched_barrier(0);
.Lhy7_odd_down:
	s_setprio 0
	s_add_i32 s98, s6, 1
	s_cmp_lg_u32 s6, 2
	s_cselect_b32 s6, s98, 0
	s_waitcnt vmcnt(6) lgkmcnt(0)
	s_barrier
	s_mul_i32 s99, s6, 0x6000
	s_setprio 1
	v_add_u32_e32 v147, s99, v141
	v_add_u32_e32 v149, s99, v143
	v_add_u32_e32 v172, v147, v145
	v_add_u32_e32 v156, v149, v145
	ds_read_b128 v[152:155], v156
	ds_read_b128 v[156:159], v156 offset:2048
	ds_read_b128 v[160:163], v172
	ds_read_b128 v[164:167], v172 offset:2048
	ds_read_b128 v[168:171], v172 offset:4096
	ds_read_b128 v[172:175], v172 offset:6144
	v_add_u32_e32 v147, v147, v138
	v_add_u32_e32 v149, v149, v138
	ds_read_b128 v[180:183], v149
	ds_read_b128 v[184:187], v149 offset:2048
	ds_read_b128 v[188:191], v147
	ds_read_b128 v[242:245], v147 offset:2048
	ds_read_b128 v[246:249], v147 offset:4096
	ds_read_b128 v[250:253], v147 offset:6144
	s_cmpk_eq_i32 s18, 0x2b80
	s_cbranch_scc1 .Lhy7_noissueO_down
	s_add_u32 s82, s74, s18
	s_addc_u32 s83, s75, s19
	s_add_i32 s84, s56, s81
	s_addk_i32 s81, 0x4000
	s_mov_b32 m0, s84
	s_nop 0
	global_load_lds_dwordx4 v1, s[82:83]
	global_load_dwordx4 v[226:229], v1, s[82:83] offset:64
	s_nop 0
	s_waitcnt lgkmcnt(9)
	s_nop 0
	v_mfma_f32_32x32x16_bf16 v[114:129], v[160:163], v[152:155], v[114:129]
	v_mfma_f32_32x32x16_bf16 v[98:113], v[160:163], v[156:159], v[98:113]
	s_add_u32 s82, s63, s18
	s_addc_u32 s83, s64, s19
	s_add_i32 s84, s81, s55
	s_mov_b32 m0, s84
	s_nop 0
	global_load_lds_dwordx4 v1, s[82:83]
	global_load_dwordx4 v[230:233], v1, s[82:83] offset:64
	s_waitcnt lgkmcnt(8)
	s_nop 0
	v_mfma_f32_32x32x16_bf16 v[82:97], v[164:167], v[152:155], v[82:97]
	v_mfma_f32_32x32x16_bf16 v[66:81], v[164:167], v[156:159], v[66:81]
	s_add_u32 s82, s60, s18
	s_addc_u32 s83, s61, s19
	s_add_i32 s81, s81, s54
	s_mov_b32 m0, s81
	s_nop 0
	global_load_lds_dwordx4 v1, s[82:83]
	global_load_dwordx4 v[234:237], v1, s[82:83] offset:64
	s_waitcnt lgkmcnt(7)
	s_nop 0
	v_mfma_f32_32x32x16_bf16 v[50:65], v[168:171], v[152:155], v[50:65]
	v_mfma_f32_32x32x16_bf16 v[34:49], v[168:171], v[156:159], v[34:49]
	s_waitcnt lgkmcnt(6)
	s_nop 0
	v_mfma_f32_32x32x16_bf16 v[18:33], v[172:175], v[152:155], v[18:33]
	v_mfma_f32_32x32x16_bf16 v[2:17], v[172:175], v[156:159], v[2:17]
	s_branch .Lhy7_afterO_down

; DEV f32x16 mfma(bf16x8 a, bf16x8 b, f32x16 c) { return __builtin_amdgcn_mfma_f32_32x32x16_bf16(a, b, c, 0, 0, 0); }
;     ...
;   for (int kt = 0; kt < nk; ++kt) {
;     if (kt + 1 < nk) { if (MI == 4) asm volatile("s_waitcnt vmcnt(6)" ::: "memory"); else asm volatile("s_waitcnt vmcnt(4)" ::: "memory"); } else asm volatile("s_waitcnt vmcnt(0)" ::: "memory");
;     __builtin_amdgcn_s_barrier();
;     if (kt + 2 < nk) { int s2 = stg + 2; if (s2 >= 3) s2 -= 3; g2_issue<MI>(ag + (size_t)(kt + 2) * 32, bg + (size_t)(kt + 2) * 32, lda, ldb, voffa, voffb, lds + s2 * G2_STAGE, w); }
;     const unsigned so = (unsigned)(stg * G2_STAGE);
;     __builtin_amdgcn_s_setprio(1);
; #pragma unroll
;     for (int ks = 0; ks < 2; ++ks) {
;       const unsigned aa = (ks ? la1 : la0) + so, bb = (ks ? lb1 : lb0) + so;
;       bf16x8 fb0, fb1, fa0, fa1, fa2, fa3;
;       asm volatile("ds_read_b128 %0, %1" : "=v"(fb0) : "v"(bb));
;       asm volatile("ds_read_b128 %0, %1 offset:2048" : "=v"(fb1) : "v"(bb));
;       asm volatile("ds_read_b128 %0, %1" : "=v"(fa0) : "v"(aa));
;       asm volatile("ds_read_b128 %0, %1 offset:2048" : "=v"(fa1) : "v"(aa));
;       if constexpr (MI == 4) {
;         asm volatile("ds_read_b128 %0, %1 offset:4096" : "=v"(fa2) : "v"(aa));
;         asm volatile("ds_read_b128 %0, %1 offset:6144" : "=v"(fa3) : "v"(aa));
;         __builtin_amdgcn_sched_barrier(0);
;         asm volatile("s_waitcnt lgkmcnt(3)" : "+v"(fb0), "+v"(fb1), "+v"(fa0));
;         acc[0][0][0] = mfma(fa0, fb0, acc[0][0][0]); acc[0][0][1] = mfma(fa0, fb1, acc[0][0][1]); __builtin_amdgcn_sched_barrier(0);
;         asm volatile("s_waitcnt lgkmcnt(2)" : "+v"(fa1));
;         acc[0][1][0] = mfma(fa1, fb0, acc[0][1][0]); acc[0][1][1] = mfma(fa1, fb1, acc[0][1][1]); __builtin_amdgcn_sched_barrier(0);
;         asm volatile("s_waitcnt lgkmcnt(1)" : "+v"(fa2));
;         acc[MI / 2 - 1][0][0] = mfma(fa2, fb0, acc[MI / 2 - 1][0][0]); acc[MI / 2 - 1][0][1] = mfma(fa2, fb1, acc[MI / 2 - 1][0][1]); __builtin_amdgcn_sched_barrier(0);
;         asm volatile("s_waitcnt lgkmcnt(0)" : "+v"(fa3));
;         acc[MI / 2 - 1][1][0] = mfma(fa3, fb0, acc[MI / 2 - 1][1][0]); acc[MI / 2 - 1][1][1] = mfma(fa3, fb1, acc[MI / 2 - 1][1][1]); __builtin_amdgcn_sched_barrier(0);
.LBB0_118:
	s_cmp_gt_i32 s80, 0
	s_cselect_b32 s81, -1, 2
	s_add_i32 s81, s81, s80
	s_mulk_i32 s81, 0x6000
	s_add_u32 s82, s6, s22
	s_addc_u32 s83, s7, s23
	s_add_i32 s84, s59, s81
	s_cmp_eq_u32 s22, 0
	s_cbranch_scc1 .Lhy7_first_up
	s_waitcnt vmcnt(0)
	s_barrier
	s_mul_i32 s99, s80, 0x6000
	s_setprio 1
	v_add_u32_e32 v149, s99, v138
	v_add_u32_e32 v176, s99, v141
	v_add_u32_e32 v172, v149, v145
	v_add_u32_e32 v156, v176, v145
	ds_read_b128 v[152:155], v156
	ds_read_b128 v[156:159], v156 offset:2048
	ds_read_b128 v[160:163], v172
	ds_read_b128 v[164:167], v172 offset:2048
	ds_read_b128 v[168:171], v172 offset:4096
	ds_read_b128 v[172:175], v172 offset:6144
	v_add_u32_e32 v238, v176, v143
	v_add_u32_e32 v149, v149, v143
	ds_read_b128 v[180:183], v238
	ds_read_b128 v[184:187], v238 offset:2048
	ds_read_b128 v[188:191], v149
	ds_read_b128 v[242:245], v149 offset:2048
	ds_read_b128 v[246:249], v149 offset:4096
	ds_read_b128 v[250:253], v149 offset:6144
	s_add_i32 s98, s80, 1
	s_cmp_lg_u32 s80, 2
	s_cselect_b32 s98, s98, 0
	s_mul_i32 s98, s98, 0x6000
	s_add_i32 s99, s59, s98
	v_add_u32_e32 v238, s99, v254
	ds_write_b128 v238, v[214:217]
	s_add_i32 s99, s58, s98
	v_add_u32_e32 v255, s99, v254
	ds_write_b128 v255, v[218:221]
	s_add_i32 s99, s57, s98
	v_add_u32_e32 v238, s99, v254
	ds_write_b128 v238, v[222:225]
	s_cmpk_eq_i32 s22, 0xf80
	s_cbranch_scc1 .Lhy7_noissueE_up
	s_mov_b32 m0, s84
	s_nop 0
	global_load_lds_dwordx4 v1, s[82:83]
	global_load_dwordx4 v[214:217], v1, s[82:83] offset:64
	s_nop 0
	s_waitcnt lgkmcnt(9)
	s_nop 0
	v_mfma_f32_32x32x16_bf16 v[114:129], v[160:163], v[152:155], v[114:129]
	v_mfma_f32_32x32x16_bf16 v[98:113], v[160:163], v[156:159], v[98:113]
	s_add_u32 s82, s78, s22
	s_addc_u32 s83, s79, s23
	s_add_i32 s84, s58, s81
	s_mov_b32 m0, s84
	s_nop 0
	global_load_lds_dwordx4 v1, s[82:83]
	global_load_dwordx4 v[218:221], v1, s[82:83] offset:64
	s_waitcnt lgkmcnt(8)
	s_nop 0
	v_mfma_f32_32x32x16_bf16 v[82:97], v[164:167], v[152:155], v[82:97]
	v_mfma_f32_32x32x16_bf16 v[66:81], v[164:167], v[156:159], v[66:81]
	s_add_u32 s82, s76, s22
	s_addc_u32 s83, s77, s23
	s_add_i32 s84, s57, s81
	s_mov_b32 m0, s84
	s_nop 0
	global_load_lds_dwordx4 v1, s[82:83]
	global_load_dwordx4 v[222:225], v1, s[82:83] offset:64
	s_waitcnt lgkmcnt(7)
	s_nop 0
	v_mfma_f32_32x32x16_bf16 v[50:65], v[168:171], v[152:155], v[50:65]
	v_mfma_f32_32x32x16_bf16 v[34:49], v[168:171], v[156:159], v[34:49]
	s_waitcnt lgkmcnt(6)
	s_nop 0
	v_mfma_f32_32x32x16_bf16 v[18:33], v[172:175], v[152:155], v[18:33]
	v_mfma_f32_32x32x16_bf16 v[2:17], v[172:175], v[156:159], v[2:17]
	s_branch .Lhy7_afterE_up

; DEV f32x16 mfma(bf16x8 a, bf16x8 b, f32x16 c) { return __builtin_amdgcn_mfma_f32_32x32x16_bf16(a, b, c, 0, 0, 0); }
;     ...
;     if (kt + 2 < nk) { int s2 = stg + 2; if (s2 >= 3) s2 -= 3; g2_issue<MI>(ag + (size_t)(kt + 2) * 32, bg + (size_t)(kt + 2) * 32, lda, ldb, voffa, voffb, lds + s2 * G2_STAGE, w); }
;     const unsigned so = (unsigned)(stg * G2_STAGE);
;     __builtin_amdgcn_s_setprio(1);
; #pragma unroll
;     for (int ks = 0; ks < 2; ++ks) {
;       const unsigned aa = (ks ? la1 : la0) + so, bb = (ks ? lb1 : lb0) + so;
;       bf16x8 fb0, fb1, fa0, fa1, fa2, fa3;
;       asm volatile("ds_read_b128 %0, %1" : "=v"(fb0) : "v"(bb));
;       asm volatile("ds_read_b128 %0, %1 offset:2048" : "=v"(fb1) : "v"(bb));
;       asm volatile("ds_read_b128 %0, %1" : "=v"(fa0) : "v"(aa));
;       asm volatile("ds_read_b128 %0, %1 offset:2048" : "=v"(fa1) : "v"(aa));
;       if constexpr (MI == 4) {
;         asm volatile("ds_read_b128 %0, %1 offset:4096" : "=v"(fa2) : "v"(aa));
;         asm volatile("ds_read_b128 %0, %1 offset:6144" : "=v"(fa3) : "v"(aa));
;         __builtin_amdgcn_sched_barrier(0);
;         asm volatile("s_waitcnt lgkmcnt(3)" : "+v"(fb0), "+v"(fb1), "+v"(fa0));
;         acc[0][0][0] = mfma(fa0, fb0, acc[0][0][0]); acc[0][0][1] = mfma(fa0, fb1, acc[0][0][1]); __builtin_amdgcn_sched_barrier(0);
;         asm volatile("s_waitcnt lgkmcnt(2)" : "+v"(fa1));
;         acc[0][1][0] = mfma(fa1, fb0, acc[0][1][0]); acc[0][1][1] = mfma(fa1, fb1, acc[0][1][1]); __builtin_amdgcn_sched_barrier(0);
;         asm volatile("s_waitcnt lgkmcnt(1)" : "+v"(fa2));
;         acc[MI / 2 - 1][0][0] = mfma(fa2, fb0, acc[MI / 2 - 1][0][0]); acc[MI / 2 - 1][0][1] = mfma(fa2, fb1, acc[MI / 2 - 1][0][1]); __builtin_amdgcn_sched_barrier(0);
;         asm volatile("s_waitcnt lgkmcnt(0)" : "+v"(fa3));
;         acc[MI / 2 - 1][1][0] = mfma(fa3, fb0, acc[MI / 2 - 1][1][0]); acc[MI / 2 - 1][1][1] = mfma(fa3, fb1, acc[MI / 2 - 1][1][1]); __builtin_amdgcn_sched_barrier(0);
.Lhy7_first_up:
	s_waitcnt vmcnt(6)
	s_barrier
	s_mul_i32 s99, s80, 0x6000
	s_setprio 1
	v_add_u32_e32 v149, s99, v138
	v_add_u32_e32 v176, s99, v141
	v_add_u32_e32 v172, v149, v145
	v_add_u32_e32 v156, v176, v145
	ds_read_b128 v[152:155], v156
	ds_read_b128 v[156:159], v156 offset:2048
	ds_read_b128 v[160:163], v172
	ds_read_b128 v[164:167], v172 offset:2048
	ds_read_b128 v[168:171], v172 offset:4096
	ds_read_b128 v[172:175], v172 offset:6144
	v_add_u32_e32 v238, v176, v143
	v_add_u32_e32 v149, v149, v143
	ds_read_b128 v[180:183], v238
	ds_read_b128 v[184:187], v238 offset:2048
	ds_read_b128 v[188:191], v149
	ds_read_b128 v[242:245], v149 offset:2048
	ds_read_b128 v[246:249], v149 offset:4096
	ds_read_b128 v[250:253], v149 offset:6144
	s_cmpk_eq_i32 s22, 0xf80
	s_cbranch_scc1 .Lhy7_noissueF_up
	s_mov_b32 m0, s84
	s_nop 0
	global_load_lds_dwordx4 v1, s[82:83]
	global_load_dwordx4 v[214:217], v1, s[82:83] offset:64
	s_nop 0
	s_waitcnt lgkmcnt(9)
	s_nop 0
	v_mfma_f32_32x32x16_bf16 v[114:129], v[160:163], v[152:155], v[114:129]
	v_mfma_f32_32x32x16_bf16 v[98:113], v[160:163], v[156:159], v[98:113]
	s_add_u32 s82, s78, s22
	s_addc_u32 s83, s79, s23
	s_add_i32 s84, s58, s81
	s_mov_b32 m0, s84
	s_nop 0
	global_load_lds_dwordx4 v1, s[82:83]
	global_load_dwordx4 v[218:221], v1, s[82:83] offset:64
	s_waitcnt lgkmcnt(8)
	s_nop 0
	v_mfma_f32_32x32x16_bf16 v[82:97], v[164:167], v[152:155], v[82:97]
	v_mfma_f32_32x32x16_bf16 v[66:81], v[164:167], v[156:159], v[66:81]
	s_add_u32 s82, s76, s22
	s_addc_u32 s83, s77, s23
	s_add_i32 s84, s57, s81
	s_mov_b32 m0, s84
	s_nop 0
	global_load_lds_dwordx4 v1, s[82:83]
	global_load_dwordx4 v[222:225], v1, s[82:83] offset:64
	s_waitcnt lgkmcnt(7)
	s_nop 0
	v_mfma_f32_32x32x16_bf16 v[50:65], v[168:171], v[152:155], v[50:65]
	v_mfma_f32_32x32x16_bf16 v[34:49], v[168:171], v[156:159], v[34:49]
	s_waitcnt lgkmcnt(6)
	s_nop 0
	v_mfma_f32_32x32x16_bf16 v[18:33], v[172:175], v[152:155], v[18:33]
	v_mfma_f32_32x32x16_bf16 v[2:17], v[172:175], v[156:159], v[2:17]
	s_branch .Lhy7_afterF_up

;     ...
;     if (kt + 1 < nk) { if (MI == 4) asm volatile("s_waitcnt vmcnt(6)" ::: "memory"); else asm volatile("s_waitcnt vmcnt(4)" ::: "memory"); } else asm volatile("s_waitcnt vmcnt(0)" ::: "memory");
;     __builtin_amdgcn_s_barrier();
;     if (kt + 2 < nk) { int s2 = stg + 2; if (s2 >= 3) s2 -= 3; g2_issue<MI>(ag + (size_t)(kt + 2) * 32, bg + (size_t)(kt + 2) * 32, lda, ldb, voffa, voffb, lds + s2 * G2_STAGE, w); }
;     const unsigned so = (unsigned)(stg * G2_STAGE);
;     __builtin_amdgcn_s_setprio(1);
; #pragma unroll
;     for (int ks = 0; ks < 2; ++ks) {
;       const unsigned aa = (ks ? la1 : la0) + so, bb = (ks ? lb1 : lb0) + so;
;       bf16x8 fb0, fb1, fa0, fa1, fa2, fa3;
;       asm volatile("ds_read_b128 %0, %1" : "=v"(fb0) : "v"(bb));
;       asm volatile("ds_read_b128 %0, %1 offset:2048" : "=v"(fb1) : "v"(bb));
;       asm volatile("ds_read_b128 %0, %1" : "=v"(fa0) : "v"(aa));
;       asm volatile("ds_read_b128 %0, %1 offset:2048" : "=v"(fa1) : "v"(aa));
;       if constexpr (MI == 4) {
;         asm volatile("ds_read_b128 %0, %1 offset:4096" : "=v"(fa2) : "v"(aa));
;         asm volatile("ds_read_b128 %0, %1 offset:6144" : "=v"(fa3) : "v"(aa));
;         __builtin_amdgcn_sched_barrier(0);
;         asm volatile("s_waitcnt lgkmcnt(3)" : "+v"(fb0), "+v"(fb1), "+v"(fa0));
;         acc[0][0][0] = mfma(fa0, fb0, acc[0][0][0]); acc[0][0][1] = mfma(fa0, fb1, acc[0][0][1]); __builtin_amdgcn_sched_barrier(0);
;         asm volatile("s_waitcnt lgkmcnt(2)" : "+v"(fa1));
;         acc[0][1][0] = mfma(fa1, fb0, acc[0][1][0]); acc[0][1][1] = mfma(fa1, fb1, acc[0][1][1]); __builtin_amdgcn_sched_barrier(0);
;         asm volatile("s_waitcnt lgkmcnt(1)" : "+v"(fa2));
;         acc[MI / 2 - 1][0][0] = mfma(fa2, fb0, acc[MI / 2 - 1][0][0]); acc[MI / 2 - 1][0][1] = mfma(fa2, fb1, acc[MI / 2 - 1][0][1]); __builtin_amdgcn_sched_barrier(0);
;         asm volatile("s_waitcnt lgkmcnt(0)" : "+v"(fa3));
;         acc[MI / 2 - 1][1][0] = mfma(fa3, fb0, acc[MI / 2 - 1][1][0]); acc[MI / 2 - 1][1][1] = mfma(fa3, fb1, acc[MI / 2 - 1][1][1]); __builtin_amdgcn_sched_barrier(0);
;       } else {
;         __builtin_amdgcn_sched_barrier(0);
;         asm volatile("s_waitcnt lgkmcnt(1)" : "+v"(fb0), "+v"(fb1), "+v"(fa0));
;         acc[0][0][0] = mfma(fa0, fb0, acc[0][0][0]); acc[0][0][1] = mfma(fa0, fb1, acc[0][0][1]); __builtin_amdgcn_sched_barrier(0);
.Lhy7_odd_up:
	s_setprio 0
	s_add_i32 s98, s80, 1
	s_cmp_lg_u32 s80, 2
	s_cselect_b32 s80, s98, 0
	s_waitcnt vmcnt(6) lgkmcnt(0)
	s_barrier
	s_mul_i32 s99, s80, 0x6000
	s_setprio 1
	v_add_u32_e32 v149, s99, v138
	v_add_u32_e32 v176, s99, v141
	v_add_u32_e32 v172, v149, v145
	v_add_u32_e32 v156, v176, v145
	ds_read_b128 v[152:155], v156
	ds_read_b128 v[156:159], v156 offset:2048
	ds_read_b128 v[160:163], v172
	ds_read_b128 v[164:167], v172 offset:2048
	ds_read_b128 v[168:171], v172 offset:4096
	ds_read_b128 v[172:175], v172 offset:6144
	v_add_u32_e32 v238, v176, v143
	v_add_u32_e32 v149, v149, v143
	ds_read_b128 v[180:183], v238
	ds_read_b128 v[184:187], v238 offset:2048
	ds_read_b128 v[188:191], v149
	ds_read_b128 v[242:245], v149 offset:2048
	ds_read_b128 v[246:249], v149 offset:4096
	ds_read_b128 v[250:253], v149 offset:6144
	s_cmpk_eq_i32 s22, 0xf80
	s_cbranch_scc1 .Lhy7_noissueO_up
	s_add_u32 s82, s74, s22
	s_addc_u32 s83, s75, s23
	s_add_i32 s84, s56, s81
	s_addk_i32 s81, 0x4000
	s_mov_b32 m0, s84
	s_nop 0
	global_load_lds_dwordx4 v1, s[82:83]
	global_load_dwordx4 v[226:229], v1, s[82:83] offset:64
	s_nop 0
	s_waitcnt lgkmcnt(9)
	s_nop 0
	v_mfma_f32_32x32x16_bf16 v[114:129], v[160:163], v[152:155], v[114:129]
	v_mfma_f32_32x32x16_bf16 v[98:113], v[160:163], v[156:159], v[98:113]
	s_add_u32 s82, s63, s22
	s_addc_u32 s83, s64, s23
	s_add_i32 s84, s81, s55
	s_mov_b32 m0, s84
	s_nop 0
	global_load_lds_dwordx4 v1, s[82:83]
	global_load_dwordx4 v[230:233], v1, s[82:83] offset:64
	s_waitcnt lgkmcnt(8)
	s_nop 0
	v_mfma_f32_32x32x16_bf16 v[82:97], v[164:167], v[152:155], v[82:97]
	v_mfma_f32_32x32x16_bf16 v[66:81], v[164:167], v[156:159], v[66:81]
	s_add_u32 s82, s60, s22
	s_addc_u32 s83, s61, s23
	s_add_i32 s81, s81, s54
	s_mov_b32 m0, s81
	s_nop 0
	global_load_lds_dwordx4 v1, s[82:83]
	global_load_dwordx4 v[234:237], v1, s[82:83] offset:64
	s_waitcnt lgkmcnt(7)
	s_nop 0
	v_mfma_f32_32x32x16_bf16 v[50:65], v[168:171], v[152:155], v[50:65]
	v_mfma_f32_32x32x16_bf16 v[34:49], v[168:171], v[156:159], v[34:49]
	s_waitcnt lgkmcnt(6)
	s_nop 0
	v_mfma_f32_32x32x16_bf16 v[18:33], v[172:175], v[152:155], v[18:33]
	v_mfma_f32_32x32x16_bf16 v[2:17], v[172:175], v[156:159], v[2:17]
	s_branch .Lhy7_afterO_up

; DEV f32x16 mfma(bf16x8 a, bf16x8 b, f32x16 c) { return __builtin_amdgcn_mfma_f32_32x32x16_bf16(a, b, c, 0, 0, 0); }
;     ...
;   for (int kt = 0; kt < nk; ++kt) {
;     if (kt + 1 < nk) { if (MI == 4) asm volatile("s_waitcnt vmcnt(6)" ::: "memory"); else asm volatile("s_waitcnt vmcnt(4)" ::: "memory"); } else asm volatile("s_waitcnt vmcnt(0)" ::: "memory");
;     __builtin_amdgcn_s_barrier();
;     if (kt + 2 < nk) { int s2 = stg + 2; if (s2 >= 3) s2 -= 3; g2_issue<MI>(ag + (size_t)(kt + 2) * 32, bg + (size_t)(kt + 2) * 32, lda, ldb, voffa, voffb, lds + s2 * G2_STAGE, w); }
;     const unsigned so = (unsigned)(stg * G2_STAGE);
;     __builtin_amdgcn_s_setprio(1);
; #pragma unroll
;     for (int ks = 0; ks < 2; ++ks) {
;       const unsigned aa = (ks ? la1 : la0) + so, bb = (ks ? lb1 : lb0) + so;
;       bf16x8 fb0, fb1, fa0, fa1, fa2, fa3;
;       asm volatile("ds_read_b128 %0, %1" : "=v"(fb0) : "v"(bb));
;       asm volatile("ds_read_b128 %0, %1 offset:2048" : "=v"(fb1) : "v"(bb));
;       asm volatile("ds_read_b128 %0, %1" : "=v"(fa0) : "v"(aa));
;       asm volatile("ds_read_b128 %0, %1 offset:2048" : "=v"(fa1) : "v"(aa));
;       if constexpr (MI == 4) {
;         asm volatile("ds_read_b128 %0, %1 offset:4096" : "=v"(fa2) : "v"(aa));
;         asm volatile("ds_read_b128 %0, %1 offset:6144" : "=v"(fa3) : "v"(aa));
;         __builtin_amdgcn_sched_barrier(0);
;         asm volatile("s_waitcnt lgkmcnt(3)" : "+v"(fb0), "+v"(fb1), "+v"(fa0));
;         acc[0][0][0] = mfma(fa0, fb0, acc[0][0][0]); acc[0][0][1] = mfma(fa0, fb1, acc[0][0][1]); __builtin_amdgcn_sched_barrier(0);
;         asm volatile("s_waitcnt lgkmcnt(2)" : "+v"(fa1));
;         acc[0][1][0] = mfma(fa1, fb0, acc[0][1][0]); acc[0][1][1] = mfma(fa1, fb1, acc[0][1][1]); __builtin_amdgcn_sched_barrier(0);
;         asm volatile("s_waitcnt lgkmcnt(1)" : "+v"(fa2));
;         acc[MI / 2 - 1][0][0] = mfma(fa2, fb0, acc[MI / 2 - 1][0][0]); acc[MI / 2 - 1][0][1] = mfma(fa2, fb1, acc[MI / 2 - 1][0][1]); __builtin_amdgcn_sched_barrier(0);
;         asm volatile("s_waitcnt lgkmcnt(0)" : "+v"(fa3));
;         acc[MI / 2 - 1][1][0] = mfma(fa3, fb0, acc[MI / 2 - 1][1][0]); acc[MI / 2 - 1][1][1] = mfma(fa3, fb1, acc[MI / 2 - 1][1][1]); __builtin_amdgcn_sched_barrier(0);
.LBB0_537:
	s_cmp_gt_i32 s79, 0
	s_cselect_b32 s80, -1, 2
	s_add_i32 s80, s80, s79
	s_mul_i32 s82, s80, 0x6000
	s_add_u32 s80, s76, s18
	s_addc_u32 s81, s77, s19
	s_add_i32 s83, s1, s82
	s_cmp_eq_u32 s18, 0
	s_cbranch_scc1 .Lhy7_first_out
	s_waitcnt vmcnt(0)
	s_barrier
	s_mul_i32 s99, s79, 0x6000
	s_setprio 1
	v_add_u32_e32 v153, s99, v138
	v_add_u32_e32 v178, s99, v141
	v_add_u32_e32 v174, v153, v147
	v_add_u32_e32 v158, v178, v147
	ds_read_b128 v[154:157], v158
	ds_read_b128 v[158:161], v158 offset:2048
	ds_read_b128 v[162:165], v174
	ds_read_b128 v[166:169], v174 offset:2048
	ds_read_b128 v[170:173], v174 offset:4096
	ds_read_b128 v[174:177], v174 offset:6144
	v_add_u32_e32 v238, v178, v145
	v_add_u32_e32 v153, v153, v145
	ds_read_b128 v[180:183], v238
	ds_read_b128 v[184:187], v238 offset:2048
	ds_read_b128 v[188:191], v153
	ds_read_b128 v[242:245], v153 offset:2048
	ds_read_b128 v[246:249], v153 offset:4096
	ds_read_b128 v[250:253], v153 offset:6144
	s_add_i32 s98, s79, 1
	s_cmp_lg_u32 s79, 2
	s_cselect_b32 s98, s98, 0
	s_mul_i32 s98, s98, 0x6000
	s_add_i32 s99, s1, s98
	v_add_u32_e32 v238, s99, v254
	ds_write_b128 v238, v[214:217]
	s_add_i32 s99, s26, s98
	v_add_u32_e32 v255, s99, v254
	ds_write_b128 v255, v[218:221]
	s_add_i32 s99, s27, s98
	v_add_u32_e32 v238, s99, v254
	ds_write_b128 v238, v[222:225]
	s_cmpk_eq_i32 s18, 0xf80
	s_cbranch_scc1 .Lhy7_noissueE_out
	s_mov_b32 m0, s83
	s_nop 0
	global_load_lds_dwordx4 v1, s[80:81]
	global_load_dwordx4 v[214:217], v1, s[80:81] offset:64
	s_nop 0
	s_waitcnt lgkmcnt(9)
	s_nop 0
	v_mfma_f32_32x32x16_bf16 v[114:129], v[162:165], v[154:157], v[114:129]
	v_mfma_f32_32x32x16_bf16 v[98:113], v[162:165], v[158:161], v[98:113]
	s_add_u32 s80, s74, s18
	s_addc_u32 s81, s75, s19
	s_add_i32 s83, s26, s82
	s_mov_b32 m0, s83
	s_nop 0
	global_load_lds_dwordx4 v1, s[80:81]
	global_load_dwordx4 v[218:221], v1, s[80:81] offset:64
	s_waitcnt lgkmcnt(8)
	s_nop 0
	v_mfma_f32_32x32x16_bf16 v[82:97], v[166:169], v[154:157], v[82:97]
	v_mfma_f32_32x32x16_bf16 v[66:81], v[166:169], v[158:161], v[66:81]
	s_add_u32 s80, s59, s18
	s_addc_u32 s81, s63, s19
	s_add_i32 s83, s27, s82
	s_mov_b32 m0, s83
	s_nop 0
	global_load_lds_dwordx4 v1, s[80:81]
	global_load_dwordx4 v[222:225], v1, s[80:81] offset:64
	s_waitcnt lgkmcnt(7)
	s_nop 0
	v_mfma_f32_32x32x16_bf16 v[50:65], v[170:173], v[154:157], v[50:65]
	v_mfma_f32_32x32x16_bf16 v[34:49], v[170:173], v[158:161], v[34:49]
	s_waitcnt lgkmcnt(6)
	s_nop 0
	v_mfma_f32_32x32x16_bf16 v[18:33], v[174:177], v[154:157], v[18:33]
	v_mfma_f32_32x32x16_bf16 v[2:17], v[174:177], v[158:161], v[2:17]
	s_branch .Lhy7_afterE_out

; DEV f32x16 mfma(bf16x8 a, bf16x8 b, f32x16 c) { return __builtin_amdgcn_mfma_f32_32x32x16_bf16(a, b, c, 0, 0, 0); }
;     ...
;     if (kt + 2 < nk) { int s2 = stg + 2; if (s2 >= 3) s2 -= 3; g2_issue<MI>(ag + (size_t)(kt + 2) * 32, bg + (size_t)(kt + 2) * 32, lda, ldb, voffa, voffb, lds + s2 * G2_STAGE, w); }
;     const unsigned so = (unsigned)(stg * G2_STAGE);
;     __builtin_amdgcn_s_setprio(1);
; #pragma unroll
;     for (int ks = 0; ks < 2; ++ks) {
;       const unsigned aa = (ks ? la1 : la0) + so, bb = (ks ? lb1 : lb0) + so;
;       bf16x8 fb0, fb1, fa0, fa1, fa2, fa3;
;       asm volatile("ds_read_b128 %0, %1" : "=v"(fb0) : "v"(bb));
;       asm volatile("ds_read_b128 %0, %1 offset:2048" : "=v"(fb1) : "v"(bb));
;       asm volatile("ds_read_b128 %0, %1" : "=v"(fa0) : "v"(aa));
;       asm volatile("ds_read_b128 %0, %1 offset:2048" : "=v"(fa1) : "v"(aa));
;       if constexpr (MI == 4) {
;         asm volatile("ds_read_b128 %0, %1 offset:4096" : "=v"(fa2) : "v"(aa));
;         asm volatile("ds_read_b128 %0, %1 offset:6144" : "=v"(fa3) : "v"(aa));
;         __builtin_amdgcn_sched_barrier(0);
;         asm volatile("s_waitcnt lgkmcnt(3)" : "+v"(fb0), "+v"(fb1), "+v"(fa0));
;         acc[0][0][0] = mfma(fa0, fb0, acc[0][0][0]); acc[0][0][1] = mfma(fa0, fb1, acc[0][0][1]); __builtin_amdgcn_sched_barrier(0);
;         asm volatile("s_waitcnt lgkmcnt(2)" : "+v"(fa1));
;         acc[0][1][0] = mfma(fa1, fb0, acc[0][1][0]); acc[0][1][1] = mfma(fa1, fb1, acc[0][1][1]); __builtin_amdgcn_sched_barrier(0);
;         asm volatile("s_waitcnt lgkmcnt(1)" : "+v"(fa2));
;         acc[MI / 2 - 1][0][0] = mfma(fa2, fb0, acc[MI / 2 - 1][0][0]); acc[MI / 2 - 1][0][1] = mfma(fa2, fb1, acc[MI / 2 - 1][0][1]); __builtin_amdgcn_sched_barrier(0);
;         asm volatile("s_waitcnt lgkmcnt(0)" : "+v"(fa3));
;         acc[MI / 2 - 1][1][0] = mfma(fa3, fb0, acc[MI / 2 - 1][1][0]); acc[MI / 2 - 1][1][1] = mfma(fa3, fb1, acc[MI / 2 - 1][1][1]); __builtin_amdgcn_sched_barrier(0);
.Lhy7_afterE_out:
	s_nop 0
	s_waitcnt lgkmcnt(6)
	s_nop 0
	v_mfma_f32_32x32x16_bf16 v[114:129], v[188:191], v[180:183], v[114:129]
	v_mfma_f32_32x32x16_bf16 v[98:113], v[188:191], v[184:187], v[98:113]
	s_waitcnt lgkmcnt(5)
	s_nop 0
	v_mfma_f32_32x32x16_bf16 v[82:97], v[242:245], v[180:183], v[82:97]
	v_mfma_f32_32x32x16_bf16 v[66:81], v[242:245], v[184:187], v[66:81]
	s_waitcnt lgkmcnt(4)
	s_nop 0
	v_mfma_f32_32x32x16_bf16 v[50:65], v[246:249], v[180:183], v[50:65]
	v_mfma_f32_32x32x16_bf16 v[34:49], v[246:249], v[184:187], v[34:49]
	s_waitcnt lgkmcnt(3)
	s_nop 0
	v_mfma_f32_32x32x16_bf16 v[18:33], v[250:253], v[180:183], v[18:33]
	v_mfma_f32_32x32x16_bf16 v[2:17], v[250:253], v[184:187], v[2:17]
	s_add_i32 s99, s28, s98
	v_add_u32_e32 v255, s99, v254
	ds_write_b128 v255, v[226:229]
	s_add_i32 s99, s30, s98
	s_addk_i32 s99, 0x4000
	v_add_u32_e32 v238, s99, v254
	ds_write_b128 v238, v[230:233]
	s_add_i32 s99, s31, s98
	s_addk_i32 s99, 0x4000
	v_add_u32_e32 v255, s99, v254
	ds_write_b128 v255, v[234:237]
	s_branch .Lhy7_odd_out
.Lhy7_first_out:
	s_waitcnt vmcnt(6)
	s_barrier
	s_mul_i32 s99, s79, 0x6000
	s_setprio 1
	v_add_u32_e32 v153, s99, v138
	v_add_u32_e32 v178, s99, v141
	v_add_u32_e32 v174, v153, v147
	v_add_u32_e32 v158, v178, v147
	ds_read_b128 v[154:157], v158
	ds_read_b128 v[158:161], v158 offset:2048
	ds_read_b128 v[162:165], v174
	ds_read_b128 v[166:169], v174 offset:2048
	ds_read_b128 v[170:173], v174 offset:4096
	ds_read_b128 v[174:177], v174 offset:6144
	v_add_u32_e32 v238, v178, v145
	v_add_u32_e32 v153, v153, v145
	ds_read_b128 v[180:183], v238
	ds_read_b128 v[184:187], v238 offset:2048
	ds_read_b128 v[188:191], v153
	ds_read_b128 v[242:245], v153 offset:2048
	ds_read_b128 v[246:249], v153 offset:4096
	ds_read_b128 v[250:253], v153 offset:6144
	s_cmpk_eq_i32 s18, 0xf80
	s_cbranch_scc1 .Lhy7_noissueF_out
	s_mov_b32 m0, s83
	s_nop 0
	global_load_lds_dwordx4 v1, s[80:81]
	global_load_dwordx4 v[214:217], v1, s[80:81] offset:64
	s_nop 0
	s_waitcnt lgkmcnt(9)
	s_nop 0
	v_mfma_f32_32x32x16_bf16 v[114:129], v[162:165], v[154:157], v[114:129]
	v_mfma_f32_32x32x16_bf16 v[98:113], v[162:165], v[158:161], v[98:113]
	s_add_u32 s80, s74, s18
	s_addc_u32 s81, s75, s19
	s_add_i32 s83, s26, s82
	s_mov_b32 m0, s83
	s_nop 0
	global_load_lds_dwordx4 v1, s[80:81]
	global_load_dwordx4 v[218:221], v1, s[80:81] offset:64
	s_waitcnt lgkmcnt(8)
	s_nop 0
	v_mfma_f32_32x32x16_bf16 v[82:97], v[166:169], v[154:157], v[82:97]
	v_mfma_f32_32x32x16_bf16 v[66:81], v[166:169], v[158:161], v[66:81]
	s_add_u32 s80, s59, s18
	s_addc_u32 s81, s63, s19
	s_add_i32 s83, s27, s82
	s_mov_b32 m0, s83
	s_nop 0
	global_load_lds_dwordx4 v1, s[80:81]
	global_load_dwordx4 v[222:225], v1, s[80:81] offset:64
	s_waitcnt lgkmcnt(7)
	s_nop 0
	v_mfma_f32_32x32x16_bf16 v[50:65], v[170:173], v[154:157], v[50:65]
	v_mfma_f32_32x32x16_bf16 v[34:49], v[170:173], v[158:161], v[34:49]
	s_waitcnt lgkmcnt(6)
	s_nop 0
	v_mfma_f32_32x32x16_bf16 v[18:33], v[174:177], v[154:157], v[18:33]
	v_mfma_f32_32x32x16_bf16 v[2:17], v[174:177], v[158:161], v[2:17]
	s_branch .Lhy7_afterF_out

;     ...
;     if (kt + 1 < nk) { if (MI == 4) asm volatile("s_waitcnt vmcnt(6)" ::: "memory"); else asm volatile("s_waitcnt vmcnt(4)" ::: "memory"); } else asm volatile("s_waitcnt vmcnt(0)" ::: "memory");
;     __builtin_amdgcn_s_barrier();
;     if (kt + 2 < nk) { int s2 = stg + 2; if (s2 >= 3) s2 -= 3; g2_issue<MI>(ag + (size_t)(kt + 2) * 32, bg + (size_t)(kt + 2) * 32, lda, ldb, voffa, voffb, lds + s2 * G2_STAGE, w); }
;     const unsigned so = (unsigned)(stg * G2_STAGE);
;     __builtin_amdgcn_s_setprio(1);
; #pragma unroll
;     for (int ks = 0; ks < 2; ++ks) {
;       const unsigned aa = (ks ? la1 : la0) + so, bb = (ks ? lb1 : lb0) + so;
;       bf16x8 fb0, fb1, fa0, fa1, fa2, fa3;
;       asm volatile("ds_read_b128 %0, %1" : "=v"(fb0) : "v"(bb));
;       asm volatile("ds_read_b128 %0, %1 offset:2048" : "=v"(fb1) : "v"(bb));
;       asm volatile("ds_read_b128 %0, %1" : "=v"(fa0) : "v"(aa));
;       asm volatile("ds_read_b128 %0, %1 offset:2048" : "=v"(fa1) : "v"(aa));
;       if constexpr (MI == 4) {
;         asm volatile("ds_read_b128 %0, %1 offset:4096" : "=v"(fa2) : "v"(aa));
;         asm volatile("ds_read_b128 %0, %1 offset:6144" : "=v"(fa3) : "v"(aa));
;         __builtin_amdgcn_sched_barrier(0);
;         asm volatile("s_waitcnt lgkmcnt(3)" : "+v"(fb0), "+v"(fb1), "+v"(fa0));
;         acc[0][0][0] = mfma(fa0, fb0, acc[0][0][0]); acc[0][0][1] = mfma(fa0, fb1, acc[0][0][1]); __builtin_amdgcn_sched_barrier(0);
;         asm volatile("s_waitcnt lgkmcnt(2)" : "+v"(fa1));
;         acc[0][1][0] = mfma(fa1, fb0, acc[0][1][0]); acc[0][1][1] = mfma(fa1, fb1, acc[0][1][1]); __builtin_amdgcn_sched_barrier(0);
;         asm volatile("s_waitcnt lgkmcnt(1)" : "+v"(fa2));
;         acc[MI / 2 - 1][0][0] = mfma(fa2, fb0, acc[MI / 2 - 1][0][0]); acc[MI / 2 - 1][0][1] = mfma(fa2, fb1, acc[MI / 2 - 1][0][1]); __builtin_amdgcn_sched_barrier(0);
;         asm volatile("s_waitcnt lgkmcnt(0)" : "+v"(fa3));
;         acc[MI / 2 - 1][1][0] = mfma(fa3, fb0, acc[MI / 2 - 1][1][0]); acc[MI / 2 - 1][1][1] = mfma(fa3, fb1, acc[MI / 2 - 1][1][1]); __builtin_amdgcn_sched_barrier(0);
;       } else {
;         __builtin_amdgcn_sched_barrier(0);
;         asm volatile("s_waitcnt lgkmcnt(1)" : "+v"(fb0), "+v"(fb1), "+v"(fa0));
;         acc[0][0][0] = mfma(fa0, fb0, acc[0][0][0]); acc[0][0][1] = mfma(fa0, fb1, acc[0][0][1]); __builtin_amdgcn_sched_barrier(0);
.Lhy7_odd_out:
	s_setprio 0
	s_add_i32 s98, s79, 1
	s_cmp_lg_u32 s79, 2
	s_cselect_b32 s79, s98, 0
	s_waitcnt vmcnt(6) lgkmcnt(0)
	s_barrier
	s_mul_i32 s99, s79, 0x6000
	s_setprio 1
	v_add_u32_e32 v153, s99, v138
	v_add_u32_e32 v178, s99, v141
	v_add_u32_e32 v174, v153, v147
	v_add_u32_e32 v158, v178, v147
	ds_read_b128 v[154:157], v158
	ds_read_b128 v[158:161], v158 offset:2048
	ds_read_b128 v[162:165], v174
	ds_read_b128 v[166:169], v174 offset:2048
	ds_read_b128 v[170:173], v174 offset:4096
	ds_read_b128 v[174:177], v174 offset:6144
	v_add_u32_e32 v238, v178, v145
	v_add_u32_e32 v153, v153, v145
	ds_read_b128 v[180:183], v238
	ds_read_b128 v[184:187], v238 offset:2048
	ds_read_b128 v[188:191], v153
	ds_read_b128 v[242:245], v153 offset:2048
	ds_read_b128 v[246:249], v153 offset:4096
	ds_read_b128 v[250:253], v153 offset:6144
	s_cmpk_eq_i32 s18, 0xf80
	s_cbranch_scc1 .Lhy7_noissueO_out
	s_add_u32 s80, s57, s18
	s_addc_u32 s81, s58, s19
	s_add_i32 s83, s28, s82
	s_addk_i32 s82, 0x4000
	s_mov_b32 m0, s83
	s_nop 0
	global_load_lds_dwordx4 v1, s[80:81]
	global_load_dwordx4 v[226:229], v1, s[80:81] offset:64
	s_nop 0
	s_waitcnt lgkmcnt(9)
	s_nop 0
	v_mfma_f32_32x32x16_bf16 v[114:129], v[162:165], v[154:157], v[114:129]
	v_mfma_f32_32x32x16_bf16 v[98:113], v[162:165], v[158:161], v[98:113]
	s_add_u32 s80, s20, s18
	s_addc_u32 s81, s21, s19
	s_add_i32 s83, s82, s30
	s_mov_b32 m0, s83
	s_nop 0
	global_load_lds_dwordx4 v1, s[80:81]
	global_load_dwordx4 v[230:233], v1, s[80:81] offset:64
	s_waitcnt lgkmcnt(8)
	s_nop 0
	v_mfma_f32_32x32x16_bf16 v[82:97], v[166:169], v[154:157], v[82:97]
	v_mfma_f32_32x32x16_bf16 v[66:81], v[166:169], v[158:161], v[66:81]
	s_add_u32 s80, s6, s18
	s_addc_u32 s81, s7, s19
	s_add_i32 s82, s82, s31
	s_mov_b32 m0, s82
	s_nop 0
	global_load_lds_dwordx4 v1, s[80:81]
	global_load_dwordx4 v[234:237], v1, s[80:81] offset:64
	s_waitcnt lgkmcnt(7)
	s_nop 0
	v_mfma_f32_32x32x16_bf16 v[50:65], v[170:173], v[154:157], v[50:65]
	v_mfma_f32_32x32x16_bf16 v[34:49], v[170:173], v[158:161], v[34:49]
	s_waitcnt lgkmcnt(6)
	s_nop 0
	v_mfma_f32_32x32x16_bf16 v[18:33], v[174:177], v[154:157], v[18:33]
	v_mfma_f32_32x32x16_bf16 v[2:17], v[174:177], v[158:161], v[2:17]
	s_branch .Lhy7_afterO_out
